# stack11 + 64-byte alignment (s_nop fill) of the 5 GEMM K-loop heads and 3 attention tile-loop heads
# speedup vs baseline: 1.0087x; 1.0084x over previous
; template <class Epi, class Sched, bool ALIGN_EPI = false, bool SP2 = false>
; __device__ __forceinline__ void gemm_phase(PG8_LAS unsigned char* lds, const Gemm g, const Sched& S, const Epi& E, int wave0) {
;     ...
;     for (;;) {
;         const bool has_next = S.next(ui + 1, nxt);
;         const char* nA = has_next ? gA + (size_t)nxt.pm * tstep + (size_t)nxt.pz * g.azs : cA; const char* nB = has_next ? gB + (size_t)nxt.pn * tstep + (size_t)nxt.pz * g.bzs : cB;
;         for (int t = 0; t < nt; t += 2) {
;             const bool last = (t == nt - 2);
;             const char* a1 = cA + (size_t)(t + 1) * kstep;
;             const char* a2 = last ? nA : cA + (size_t)(t + 2) * kstep; const char* b2 = last ? nB : cB + (size_t)(t + 2) * kstep;
;     ...
;         else if (!keep_acc)
; #pragma unroll
;         for (int a = 0; a < 2; ++a)
; #pragma unroll
;             for (int b = 0; b < 2; ++b)
; #pragma unroll
;                 for (int m = 0; m < 4; ++m)
; #pragma unroll
;                     for (int n = 0; n < 2; ++n) acc[a][b][m][n] = (f32x4){0.f, 0.f, 0.f, 0.f};
;         cur = nxt; cA = nA; cB = nB; ++ui;
.LBB0_194:
	s_ashr_i32 s53, s52, 31
	s_lshl_b64 s[42:43], s[52:53], 19
	s_add_u32 s54, s33, s42
	s_addc_u32 s55, s58, s43
	s_and_b64 s[42:43], s[40:41], exec
	s_cselect_b32 s44, s55, s1
	s_cselect_b32 s53, s54, s0
	s_ashr_i32 s51, s50, 31
	s_lshl_b64 s[42:43], s[50:51], 19
	s_add_u32 s56, s59, s42
	s_addc_u32 s57, s60, s43
	s_and_b64 s[42:43], s[40:41], exec
	s_cselect_b32 s51, s57, s5
	s_cselect_b32 s82, s56, s4
	s_add_u32 s0, s0, 0x40080
	s_addc_u32 s1, s1, 0
	s_add_u32 s83, s4, 0x100
	v_mov_b32_e32 v2, 0
	s_addc_u32 s84, s5, 0
	s_mov_b32 s85, -2
	v_mov_b32_e32 v3, v2
	v_mov_b32_e32 v4, v2
	v_mov_b32_e32 v5, v2
	v_mov_b32_e32 v6, v2
	v_mov_b32_e32 v7, v2
	v_mov_b32_e32 v8, v2
	v_mov_b32_e32 v9, v2
	s_waitcnt vmcnt(0)
	v_mov_b32_e32 v18, v2
	v_mov_b32_e32 v19, v2
	v_mov_b32_e32 v20, v2
	v_mov_b32_e32 v21, v2
	v_mov_b32_e32 v22, v2
	v_mov_b32_e32 v23, v2
	v_mov_b32_e32 v24, v2
	v_mov_b32_e32 v25, v2
	v_mov_b32_e32 v34, v2
	v_mov_b32_e32 v35, v2
	v_mov_b32_e32 v36, v2
	v_mov_b32_e32 v37, v2
	v_mov_b32_e32 v38, v2
	v_mov_b32_e32 v39, v2
	v_mov_b32_e32 v40, v2
	v_mov_b32_e32 v41, v2
	v_mov_b32_e32 v50, v2
	v_mov_b32_e32 v51, v2
	v_mov_b32_e32 v52, v2
	v_mov_b32_e32 v53, v2
	v_mov_b32_e32 v54, v2
	v_mov_b32_e32 v55, v2
	v_mov_b32_e32 v56, v2
	v_mov_b32_e32 v57, v2
	v_mov_b32_e32 v10, v2
	v_mov_b32_e32 v11, v2
	v_mov_b32_e32 v12, v2
	v_mov_b32_e32 v13, v2
	v_mov_b32_e32 v14, v2
	v_mov_b32_e32 v15, v2
	v_mov_b32_e32 v16, v2
	v_mov_b32_e32 v17, v2
	v_mov_b32_e32 v26, v2
	v_mov_b32_e32 v27, v2
	v_mov_b32_e32 v28, v2
	v_mov_b32_e32 v29, v2
	v_mov_b32_e32 v30, v2
	v_mov_b32_e32 v31, v2
	v_mov_b32_e32 v32, v2
	v_mov_b32_e32 v33, v2
	v_mov_b32_e32 v42, v2
	v_mov_b32_e32 v43, v2
	v_mov_b32_e32 v44, v2
	v_mov_b32_e32 v45, v2
	v_mov_b32_e32 v46, v2
	v_mov_b32_e32 v47, v2
	v_mov_b32_e32 v48, v2
	v_mov_b32_e32 v49, v2
	v_mov_b32_e32 v58, v2
	v_mov_b32_e32 v59, v2
	v_mov_b32_e32 v60, v2
	v_mov_b32_e32 v61, v2
	v_mov_b32_e32 v62, v2
	v_mov_b32_e32 v63, v2
	v_mov_b32_e32 v64, v2
	v_mov_b32_e32 v65, v2
	v_mov_b32_e32 v66, v2
	v_mov_b32_e32 v67, v2
	v_mov_b32_e32 v68, v2
	v_mov_b32_e32 v69, v2
	v_mov_b32_e32 v70, v2
	v_mov_b32_e32 v71, v2
	v_mov_b32_e32 v72, v2
	v_mov_b32_e32 v73, v2
	v_mov_b32_e32 v82, v2
	v_mov_b32_e32 v83, v2
	v_mov_b32_e32 v84, v2
	v_mov_b32_e32 v85, v2
	v_mov_b32_e32 v86, v2
	v_mov_b32_e32 v87, v2
	v_mov_b32_e32 v88, v2
	v_mov_b32_e32 v89, v2
	v_mov_b32_e32 v98, v2
	v_mov_b32_e32 v99, v2
	v_mov_b32_e32 v100, v2
	v_mov_b32_e32 v101, v2
	v_mov_b32_e32 v102, v2
	v_mov_b32_e32 v103, v2
	v_mov_b32_e32 v104, v2
	v_mov_b32_e32 v105, v2
	v_mov_b32_e32 v114, v2
	v_mov_b32_e32 v115, v2
	v_mov_b32_e32 v116, v2
	v_mov_b32_e32 v117, v2
	v_mov_b32_e32 v118, v2
	v_mov_b32_e32 v119, v2
	v_mov_b32_e32 v120, v2
	v_mov_b32_e32 v121, v2
	v_mov_b32_e32 v74, v2
	v_mov_b32_e32 v75, v2
	v_mov_b32_e32 v76, v2
	v_mov_b32_e32 v77, v2
	v_mov_b32_e32 v78, v2
	v_mov_b32_e32 v79, v2
	v_mov_b32_e32 v80, v2
	v_mov_b32_e32 v81, v2
	v_mov_b32_e32 v90, v2
	v_mov_b32_e32 v91, v2
	v_mov_b32_e32 v92, v2
	v_mov_b32_e32 v93, v2
	v_mov_b32_e32 v94, v2
	v_mov_b32_e32 v95, v2
	v_mov_b32_e32 v96, v2
	v_mov_b32_e32 v97, v2
	v_mov_b32_e32 v106, v2
	v_mov_b32_e32 v107, v2
	v_mov_b32_e32 v108, v2
	v_mov_b32_e32 v109, v2
	v_mov_b32_e32 v110, v2
	v_mov_b32_e32 v111, v2
	v_mov_b32_e32 v112, v2
	v_mov_b32_e32 v113, v2
	v_mov_b32_e32 v122, v2
	v_mov_b32_e32 v123, v2
	v_mov_b32_e32 v124, v2
	v_mov_b32_e32 v125, v2
	v_mov_b32_e32 v126, v2
	v_mov_b32_e32 v127, v2
	v_mov_b32_e32 v128, v2
	v_mov_b32_e32 v129, v2
	.p2alignl 6, 3212836864

; #define ATT_LOAD(t, S) do { const int tl_ = (t) < u_hi ? (t) : u_hi;     \
;         k##S = *(const u32x4*)(kg + (size_t)tl_ * 64 * 512); v##S = *(const u32x4*)(vg + (size_t)tl_ * 64 * 512); \
;         if (TYPE == 1) k2##S = *(const u32x4*)(krg + (size_t)tl_ * 64 * 32); if (TYPE == 0) cb##S = cg_[tl_ * 64]; } while (0)
; template <int TYPE> __device__ __forceinline__ int unit(const P& p, LAS unsigned char* lds, int b, int h, int qb, int wave0, bool pre, unsigned nx, int G,
;         u32x4& kA, u32x4& vA, u32x4& k2A, float& cbA, u32x4& kB, u32x4& vB, u32x4& k2B, float& cbB) {
;     ...
;     for (; t < u_hi - 1; t += 2) {
;         ATT_LOAD(t + 2, A);
;         if (t >= w_lo && t <= w_hi) tile<TYPE, ND0, KSTR>(lds, 0, t, w_lo, w_hi, n, qrel, lane, r32, hi, qr, m_run, l_run, o0, o1, negm);
;         ATT_STORE(1, B);
;         __syncthreads();
;         ATT_LOAD(t + 3, B);
;         if (t + 1 >= w_lo && t + 1 <= w_hi) tile<TYPE, ND0, KSTR>(lds, 1, t + 1, w_lo, w_hi, n, qrel, lane, r32, hi, qr, m_run, l_run, o0, o1, negm);
;         ATT_STORE(0, A);
;         if (t == u_lo && tid == 0) tk[0] = G + (int)nx;
;         __syncthreads();
;     }
.LBB0_606:
	s_or_b64 exec, exec, s[4:5]
	s_add_i32 s29, s29, 2
	s_add_i32 s2, s9, s29
	s_add_i32 s38, s38, -2
	s_add_i32 s3, s2, -2
	s_cmp_lt_i32 s3, s8
	v_add_u32_e32 v247, 0xfffffe00, v247
	s_waitcnt lgkmcnt(0)
	s_barrier
	s_cbranch_scc0 .LBB0_631
	.p2alignl 6, 3212836864

; __device__ __forceinline__ int crow(int r, int hi) { return (r & 3) + 8 * (r >> 2) + 4 * hi; }
; #define ATT_LOAD(t, S) do { const int tl_ = (t) < u_hi ? (t) : u_hi;     \
;         k##S = *(const u32x4*)(kg + (size_t)tl_ * 64 * 512); v##S = *(const u32x4*)(vg + (size_t)tl_ * 64 * 512); \
;         if (TYPE == 1) k2##S = *(const u32x4*)(krg + (size_t)tl_ * 64 * 32); if (TYPE == 0) cb##S = cg_[tl_ * 64]; } while (0)
; template <int TYPE, int ND0, int KSTR> __device__ __forceinline__ void tile(LAS unsigned char* lds, int buf, int t, int w_lo, int w_hi, int n, int qrel, int lane, int r32, int hi,
;         const bf16x8 (&qr)[ND0], float& m_run, float& l_run, f32x16& o0, f32x16& o1, f32x16& negm) {
;     ...
;         if (t == w_hi) {
; #pragma unroll
;             for (int r = 0; r < 16; ++r) { const int kr_ = crow(r, hi); if (kr_ > qrel) p0[r] = -1e30f; if (kr_ + 32 > qrel) p1[r] = -1e30f; }
;         }
; template <int TYPE> __device__ __forceinline__ int unit(const P& p, LAS unsigned char* lds, int b, int h, int qb, int wave0, bool pre, unsigned nx, int G,
;         u32x4& kA, u32x4& vA, u32x4& k2A, float& cbA, u32x4& kB, u32x4& vB, u32x4& k2B, float& cbB) {
;     ...
;     float m_run = 0.f, l_run = 0.f; f32x16 o0 = {}, o1 = {};
;     f32x16 negm;
; #pragma unroll
;     for (int r = 0; r < 16; ++r) negm[r] = 0.f;
;     if (!pre) { ATT_LOAD(u_lo, A); ATT_LOAD(u_lo + 1, B); }
;     ATT_STORE(0, A);
;     __syncthreads();
;     const int qrel = 32 * (w & 1) + r32;
;     int t = u_lo;
;     for (; t < u_hi - 1; t += 2) {
.LBB0_656:
	s_or_b64 exec, exec, s[0:1]
	v_lshrrev_b32_e32 v244, 2, v230
	v_lshlrev_b32_e32 v218, 2, v13
	v_and_or_b32 v2, v244, 3, v218
	s_waitcnt vmcnt(2)
	v_mad_u32_u24 v239, v2, s27, 0
	v_and_b32_e32 v2, 16, v230
	v_and_or_b32 v2, v180, 12, v2
	v_and_or_b32 v0, s2, 32, v12
	v_lshlrev_b32_e32 v243, 1, v2
	v_or_b32_e32 v2, 32, v218
	v_cmp_gt_u32_e64 s[46:47], v2, v0
	v_or_b32_e32 v2, 33, v218
	v_cmp_gt_u32_e64 s[48:49], v2, v0
	v_or_b32_e32 v2, 2, v218
	v_cmp_gt_u32_e64 s[50:51], v2, v0
	v_or_b32_e32 v2, 34, v218
	v_cmp_gt_u32_e64 s[52:53], v2, v0
	v_or_b32_e32 v2, 3, v218
	v_cmp_gt_u32_e64 s[54:55], v2, v0
	v_or_b32_e32 v2, 35, v218
	v_cmp_gt_u32_e64 s[56:57], v2, v0
	v_or_b32_e32 v2, 8, v218
	v_cmp_gt_u32_e64 s[58:59], v2, v0
	v_or_b32_e32 v2, 40, v218
	v_cmp_gt_u32_e64 s[60:61], v2, v0
	v_or_b32_e32 v2, 9, v218
	v_cmp_gt_u32_e64 s[62:63], v2, v0
	v_or_b32_e32 v2, 41, v218
	v_cmp_gt_u32_e64 s[64:65], v2, v0
	v_or_b32_e32 v2, 10, v218
	v_cmp_gt_u32_e64 s[66:67], v2, v0
	v_or_b32_e32 v2, 42, v218
	v_cmp_gt_u32_e64 s[68:69], v2, v0
	v_or_b32_e32 v2, 11, v218
	v_cmp_gt_u32_e64 s[70:71], v2, v0
	v_or_b32_e32 v2, 43, v218
	v_cmp_gt_u32_e64 s[74:75], v2, v0
	v_or_b32_e32 v2, 16, v218
	v_cmp_gt_u32_e64 s[76:77], v2, v0
	v_or_b32_e32 v2, 48, v218
	v_cmp_gt_u32_e64 s[78:79], v2, v0
	v_or_b32_e32 v2, 17, v218
	v_cmp_gt_u32_e64 s[80:81], v2, v0
	v_or_b32_e32 v2, 49, v218
	v_cmp_gt_u32_e64 s[82:83], v2, v0
	v_or_b32_e32 v2, 18, v218
	v_cmp_gt_u32_e64 s[84:85], v2, v0
	v_or_b32_e32 v2, 50, v218
	v_cmp_gt_u32_e64 s[86:87], v2, v0
	v_or_b32_e32 v2, 19, v218
	v_cmp_gt_u32_e64 s[88:89], v2, v0
	v_or_b32_e32 v2, 51, v218
	v_cmp_gt_u32_e64 s[90:91], v2, v0
	v_or_b32_e32 v2, 24, v218
	v_cmp_gt_u32_e64 s[92:93], v2, v0
	v_or_b32_e32 v2, 56, v218
	v_cmp_gt_u32_e64 s[94:95], v2, v0
	v_or_b32_e32 v2, 25, v218
	s_movk_i32 s0, 0x90
	v_cmp_gt_u32_e64 s[96:97], v2, v0
	v_or_b32_e32 v2, 57, v218
	v_mad_u32_u24 v173, v12, s0, 0
	v_cmp_gt_u32_e64 s[0:1], v2, v0
	v_or_b32_e32 v2, 26, v218
	v_cmp_gt_u32_e64 s[4:5], v2, v0
	v_or_b32_e32 v2, 58, v218
	v_cmp_gt_u32_e64 s[6:7], v2, v0
	v_or_b32_e32 v2, 27, v218
	v_lshlrev_b32_e32 v245, 3, v14
	s_ashr_i32 s3, s3, 7
	s_lshl_b32 s25, s33, 2
	v_cmp_gt_u32_e64 s[8:9], v2, v0
	v_or_b32_e32 v2, 59, v218
	s_lshl_b32 s2, s28, 2
	v_mov_b32_e32 v14, v1
	v_mov_b32_e32 v15, v1
	v_lshlrev_b64 v[176:177], 9, v[10:11]
	s_add_i32 s41, s3, s25
	v_cmp_gt_u32_e64 s[42:43], v218, v0
	v_cmp_lt_u32_e64 s[38:39], v218, v0
	v_cmp_gt_u32_e64 s[72:73], v2, v0
	s_add_i32 s3, s3, s2
	v_mov_b32_e32 v0, v1
	v_mov_b32_e32 v2, v1
	v_mov_b32_e32 v3, v1
	v_mov_b32_e32 v4, v1
	v_mov_b32_e32 v5, v1
	v_mov_b32_e32 v6, v1
	v_mov_b32_e32 v7, v1
	v_mov_b32_e32 v8, v1
	v_mov_b32_e32 v9, v1
	v_mov_b32_e32 v10, v1
	v_mov_b32_e32 v11, v1
	v_mov_b32_e32 v12, v1
	v_mov_b32_e32 v13, v1
	v_mov_b64_e32 v[46:47], v[14:15]
	v_mov_b64_e32 v[30:31], v[14:15]
	v_mov_b64_e32 v[62:63], v[14:15]
	v_add_u32_e32 v231, 0, v172
	s_waitcnt vmcnt(0)
	v_add_u32_e32 v246, s26, v250
	s_mov_b32 s28, 0
	s_sub_i32 s30, 0, s3
	v_mov_b32_e32 v178, 0
	s_mov_b32 s29, -2
	v_mov_b64_e32 v[44:45], v[12:13]
	v_mov_b64_e32 v[42:43], v[10:11]
	v_mov_b64_e32 v[40:41], v[8:9]
	v_mov_b64_e32 v[38:39], v[6:7]
	v_mov_b64_e32 v[36:37], v[4:5]
	v_mov_b64_e32 v[34:35], v[2:3]
	v_mov_b64_e32 v[32:33], v[0:1]
	v_mov_b64_e32 v[28:29], v[12:13]
	v_mov_b64_e32 v[26:27], v[10:11]
	v_mov_b64_e32 v[24:25], v[8:9]
	v_mov_b64_e32 v[22:23], v[6:7]
	v_mov_b64_e32 v[20:21], v[4:5]
	v_mov_b64_e32 v[18:19], v[2:3]
	v_mov_b64_e32 v[16:17], v[0:1]
	v_mov_b64_e32 v[60:61], v[12:13]
	v_mov_b64_e32 v[58:59], v[10:11]
	v_mov_b64_e32 v[56:57], v[8:9]
	v_mov_b64_e32 v[54:55], v[6:7]
	v_mov_b64_e32 v[52:53], v[4:5]
	v_mov_b64_e32 v[50:51], v[2:3]
	v_mov_b64_e32 v[48:49], v[0:1]
	v_mov_b32_e32 v181, 0
	s_waitcnt lgkmcnt(0)
	s_barrier
	.p2alignl 6, 3212836864

; #define LAS __attribute__((address_space(3)))
; #define ATT_LOAD(t, S) do { const int tl_ = (t) < u_hi ? (t) : u_hi;     \
;         k##S = *(const u32x4*)(kg + (size_t)tl_ * 64 * 512); v##S = *(const u32x4*)(vg + (size_t)tl_ * 64 * 512); \
;         if (TYPE == 1) k2##S = *(const u32x4*)(krg + (size_t)tl_ * 64 * 32); if (TYPE == 0) cb##S = cg_[tl_ * 64]; } while (0)
; template <int TYPE, int ND0, int KSTR> __device__ __forceinline__ void tile(LAS unsigned char* lds, int buf, int t, int w_lo, int w_hi, int n, int qrel, int lane, int r32, int hi,
;         const bf16x8 (&qr)[ND0], float& m_run, float& l_run, f32x16& o0, f32x16& o1, f32x16& negm) {
;     const LAS unsigned char* kb = lds + KOFF + buf * KBUF + r32 * KSTR + hi * 16;
;     bf16x8 ka[ND0], kc[ND0];
; #pragma unroll
;     for (int d0 = 0; d0 < ND0; ++d0) { ka[d0] = *(const LAS bf16x8*)(kb + d0 * 32); kc[d0] = *(const LAS bf16x8*)(kb + 32 * KSTR + d0 * 32); }
;     const LAS unsigned char* vb = lds + VOFF + buf * VBUF + (4 * hi + ((lane & 15) >> 2)) * VSTR + (16 * ((lane >> 4) & 1) + 4 * (lane & 3)) * 2;
; template <int TYPE> __device__ __forceinline__ int unit(const P& p, LAS unsigned char* lds, int b, int h, int qb, int wave0, bool pre, unsigned nx, int G,
;         u32x4& kA, u32x4& vA, u32x4& k2A, float& cbA, u32x4& kB, u32x4& vB, u32x4& k2B, float& cbB) {
;     ...
;     float m_run = 0.f, l_run = 0.f; f32x16 o0 = {}, o1 = {};
;     f32x16 negm;
; #pragma unroll
;     for (int r = 0; r < 16; ++r) negm[r] = 0.f;
;     if (!pre) { ATT_LOAD(u_lo, A); ATT_LOAD(u_lo + 1, B); }
;     ATT_STORE(0, A);
;     __syncthreads();
;     const int qrel = 32 * (w & 1) + r32;
;     int t = u_lo;
;     for (; t < u_hi - 1; t += 2) {
.LBB0_703:
	s_or_b64 exec, exec, s[4:5]
	v_lshlrev_b32_e32 v218, 2, v3
	v_and_b32_e32 v178, 63, v226
	v_mad_u32_u24 v227, v2, s10, 0
	v_and_or_b32 v2, v6, 3, v218
	s_movk_i32 s4, 0xc0
	v_mad_u32_u24 v228, v2, s4, 0
	v_and_b32_e32 v2, 16, v226
	v_lshlrev_b32_e32 v3, 2, v178
	v_and_or_b32 v2, v3, 12, v2
	v_mov_b32_e32 v14, v1
	v_mov_b32_e32 v15, v1
	v_lshlrev_b32_e32 v231, 3, v4
	v_lshlrev_b32_e32 v230, 3, v5
	s_ashr_i32 s9, s2, 7
	s_lshl_b32 s2, s33, 2
	v_lshlrev_b32_e32 v229, 1, v2
	v_add_u32_e32 v225, 0, v0
	v_mov_b32_e32 v0, v1
	v_mov_b32_e32 v2, v1
	v_mov_b32_e32 v3, v1
	v_mov_b32_e32 v4, v1
	v_mov_b32_e32 v5, v1
	v_mov_b32_e32 v6, v1
	v_mov_b32_e32 v7, v1
	v_mov_b32_e32 v8, v1
	v_mov_b32_e32 v9, v1
	v_mov_b32_e32 v10, v1
	v_mov_b32_e32 v11, v1
	v_mov_b32_e32 v12, v1
	v_mov_b32_e32 v13, v1
	v_mov_b64_e32 v[46:47], v[14:15]
	v_mov_b64_e32 v[30:31], v[14:15]
	v_mov_b64_e32 v[62:63], v[14:15]
	s_lshl_b32 s8, s24, 6
	s_add_i32 s9, s9, s2
	s_waitcnt vmcnt(0)
	v_add_u32_e32 v219, s26, v250
	s_mov_b32 s3, 0
	v_mov_b32_e32 v166, 0
	v_mov_b64_e32 v[44:45], v[12:13]
	v_mov_b64_e32 v[42:43], v[10:11]
	v_mov_b64_e32 v[40:41], v[8:9]
	v_mov_b64_e32 v[38:39], v[6:7]
	v_mov_b64_e32 v[36:37], v[4:5]
	v_mov_b64_e32 v[34:35], v[2:3]
	v_mov_b64_e32 v[32:33], v[0:1]
	v_mov_b64_e32 v[28:29], v[12:13]
	v_mov_b64_e32 v[26:27], v[10:11]
	v_mov_b64_e32 v[24:25], v[8:9]
	v_mov_b64_e32 v[22:23], v[6:7]
	v_mov_b64_e32 v[20:21], v[4:5]
	v_mov_b64_e32 v[18:19], v[2:3]
	v_mov_b64_e32 v[16:17], v[0:1]
	v_mov_b64_e32 v[60:61], v[12:13]
	v_mov_b64_e32 v[58:59], v[10:11]
	v_mov_b64_e32 v[56:57], v[8:9]
	v_mov_b64_e32 v[54:55], v[6:7]
	v_mov_b64_e32 v[52:53], v[4:5]
	v_mov_b64_e32 v[50:51], v[2:3]
	v_mov_b64_e32 v[48:49], v[0:1]
	v_mov_b32_e32 v171, 0
	s_waitcnt lgkmcnt(0)
	s_barrier
	.p2alignl 6, 3212836864

; template <class Epi, class Sched, bool ALIGN_EPI = false, bool SP2 = false>
; __device__ __forceinline__ void gemm_phase(PG8_LAS unsigned char* lds, const Gemm g, const Sched& S, const Epi& E, int wave0) {
;     ...
;         const bool has_next = S.next(ui + 1, nxt);
;         const char* nA = has_next ? gA + (size_t)nxt.pm * tstep + (size_t)nxt.pz * g.azs : cA; const char* nB = has_next ? gB + (size_t)nxt.pn * tstep + (size_t)nxt.pz * g.bzs : cB;
;         for (int t = 0; t < nt; t += 2) {
;             const bool last = (t == nt - 2);
;             const char* a1 = cA + (size_t)(t + 1) * kstep;
;             const char* a2 = last ? nA : cA + (size_t)(t + 2) * kstep; const char* b2 = last ? nB : cB + (size_t)(t + 2) * kstep;
;             const char* a3 = a2 + kstep; const char* b3 = b2 + kstep;
.LBB0_811:
	s_mul_i32 s23, s25, -3
	s_ashr_i32 s25, s24, 31
	s_add_i32 s30, s23, s59
	s_lshl_b64 s[28:29], s[24:25], 18
	s_add_u32 s23, s2, s28
	s_addc_u32 s25, s3, s29
	s_ashr_i32 s31, s30, 31
	s_lshl_b64 s[28:29], s[30:31], 24
	s_add_u32 s38, s23, s28
	s_addc_u32 s39, s25, s29
	s_and_b64 s[28:29], s[42:43], exec
	s_cselect_b32 s25, s39, s1
	s_cselect_b32 s63, s38, s0
	s_ashr_i32 s23, s22, 31
	s_lshl_b64 s[28:29], s[22:23], 18
	s_add_u32 s23, s33, s28
	s_addc_u32 s36, s44, s29
	s_lshl_b64 s[28:29], s[30:31], 20
	s_add_u32 s28, s23, s28
	s_addc_u32 s29, s36, s29
	s_and_b64 s[46:47], s[42:43], exec
	s_cselect_b32 s23, s29, s5
	s_cselect_b32 s31, s28, s4
	s_add_u32 s0, s0, 0x20080
	s_addc_u32 s1, s1, 0
	s_add_u32 s64, s4, 0x100
	s_addc_u32 s65, s5, 0
	s_mov_b32 s66, -2
	.p2alignl 6, 3212836864

; template <class Epi, class Sched, bool ALIGN_EPI = false, bool SP2 = false>
; __device__ __forceinline__ void gemm_phase(PG8_LAS unsigned char* lds, const Gemm g, const Sched& S, const Epi& E, int wave0) {
;     ...
;         const bool has_next = S.next(ui + 1, nxt);
;         const char* nA = has_next ? gA + (size_t)nxt.pm * tstep + (size_t)nxt.pz * g.azs : cA; const char* nB = has_next ? gB + (size_t)nxt.pn * tstep + (size_t)nxt.pz * g.bzs : cB;
;         for (int t = 0; t < nt; t += 2) {
;             const bool last = (t == nt - 2);
;             const char* a1 = cA + (size_t)(t + 1) * kstep;
;             const char* a2 = last ? nA : cA + (size_t)(t + 2) * kstep; const char* b2 = last ? nB : cB + (size_t)(t + 2) * kstep;
;             const char* a3 = a2 + kstep; const char* b3 = b2 + kstep;
.LBB0_996:
	s_ashr_i32 s31, s30, 31
	s_lshl_b64 s[38:39], s[30:31], 19
	s_add_u32 s38, s2, s38
	s_addc_u32 s39, s3, s39
	s_and_b64 s[42:43], s[0:1], exec
	s_cselect_b32 s31, s39, s47
	s_cselect_b32 s63, s38, s46
	s_ashr_i32 s25, s24, 31
	s_lshl_b64 s[42:43], s[24:25], 19
	s_add_u32 s42, s50, s42
	s_addc_u32 s43, s51, s43
	s_and_b64 s[48:49], s[0:1], exec
	s_cselect_b32 s25, s43, s29
	s_cselect_b32 s64, s42, s28
	s_add_u32 s46, s46, 0x40080
	s_addc_u32 s47, s47, 0
	s_add_u32 s65, s28, 0x100
	s_addc_u32 s66, s29, 0
	s_mov_b32 s67, -2
	s_waitcnt vmcnt(0)
	.p2alignl 6, 3212836864

; template <class Epi, class Sched, bool ALIGN_EPI = false, bool SP2 = false>
; __device__ __forceinline__ void gemm_phase(PG8_LAS unsigned char* lds, const Gemm g, const Sched& S, const Epi& E, int wave0) {
;     ...
;         const bool has_next = S.next(ui + 1, nxt);
;         const char* nA = has_next ? gA + (size_t)nxt.pm * tstep + (size_t)nxt.pz * g.azs : cA; const char* nB = has_next ? gB + (size_t)nxt.pn * tstep + (size_t)nxt.pz * g.bzs : cB;
;         for (int t = 0; t < nt; t += 2) {
;             const bool last = (t == nt - 2);
;             const char* a1 = cA + (size_t)(t + 1) * kstep;
;             const char* a2 = last ? nA : cA + (size_t)(t + 2) * kstep; const char* b2 = last ? nB : cB + (size_t)(t + 2) * kstep;
;             const char* a3 = a2 + kstep; const char* b3 = b2 + kstep;
;     ...
;         else if (!keep_acc)
; #pragma unroll
;         for (int a = 0; a < 2; ++a)
; #pragma unroll
;             for (int b = 0; b < 2; ++b)
; #pragma unroll
;                 for (int m = 0; m < 4; ++m)
; #pragma unroll
;                     for (int n = 0; n < 2; ++n) acc[a][b][m][n] = (f32x4){0.f, 0.f, 0.f, 0.f};
;         cur = nxt; cA = nA; cB = nB; ++ui;
.LBB0_1110:
	s_ashr_i32 s23, s22, 31
	s_lshl_b64 s[24:25], s[22:23], 19
	s_add_u32 s24, s2, s24
	s_addc_u32 s25, s3, s25
	s_and_b64 s[30:31], s[0:1], exec
	s_cselect_b32 s23, s25, s29
	s_cselect_b32 s60, s24, s28
	s_ashr_i32 s21, s20, 31
	s_lshl_b64 s[30:31], s[20:21], 19
	s_add_u32 s30, s33, s30
	s_addc_u32 s31, s44, s31
	s_and_b64 s[42:43], s[0:1], exec
	s_cselect_b32 s21, s31, s39
	s_cselect_b32 s61, s30, s38
	s_add_u32 s28, s28, 0x40080
	s_addc_u32 s29, s29, 0
	s_add_u32 s62, s38, 0x100
	v_mov_b32_e32 v2, 0
	s_addc_u32 s63, s39, 0
	s_mov_b32 s64, -2
	v_mov_b32_e32 v3, v2
	v_mov_b32_e32 v4, v2
	v_mov_b32_e32 v5, v2
	v_mov_b32_e32 v6, v2
	v_mov_b32_e32 v7, v2
	v_mov_b32_e32 v8, v2
	v_mov_b32_e32 v9, v2
	v_mov_b32_e32 v18, v2
	v_mov_b32_e32 v19, v2
	v_mov_b32_e32 v20, v2
	v_mov_b32_e32 v21, v2
	v_mov_b32_e32 v22, v2
	v_mov_b32_e32 v23, v2
	v_mov_b32_e32 v24, v2
	v_mov_b32_e32 v25, v2
	v_mov_b32_e32 v34, v2
	v_mov_b32_e32 v35, v2
	v_mov_b32_e32 v36, v2
	v_mov_b32_e32 v37, v2
	v_mov_b32_e32 v38, v2
	v_mov_b32_e32 v39, v2
	v_mov_b32_e32 v40, v2
	v_mov_b32_e32 v41, v2
	v_mov_b32_e32 v50, v2
	v_mov_b32_e32 v51, v2
	v_mov_b32_e32 v52, v2
	v_mov_b32_e32 v53, v2
	v_mov_b32_e32 v54, v2
	v_mov_b32_e32 v55, v2
	v_mov_b32_e32 v56, v2
	v_mov_b32_e32 v57, v2
	v_mov_b32_e32 v10, v2
	v_mov_b32_e32 v11, v2
	v_mov_b32_e32 v12, v2
	v_mov_b32_e32 v13, v2
	v_mov_b32_e32 v14, v2
	v_mov_b32_e32 v15, v2
	v_mov_b32_e32 v16, v2
	v_mov_b32_e32 v17, v2
	v_mov_b32_e32 v26, v2
	v_mov_b32_e32 v27, v2
	v_mov_b32_e32 v28, v2
	v_mov_b32_e32 v29, v2
	v_mov_b32_e32 v30, v2
	v_mov_b32_e32 v31, v2
	v_mov_b32_e32 v32, v2
	v_mov_b32_e32 v33, v2
	v_mov_b32_e32 v42, v2
	v_mov_b32_e32 v43, v2
	v_mov_b32_e32 v44, v2
	v_mov_b32_e32 v45, v2
	v_mov_b32_e32 v46, v2
	v_mov_b32_e32 v47, v2
	v_mov_b32_e32 v48, v2
	v_mov_b32_e32 v49, v2
	v_mov_b32_e32 v58, v2
	v_mov_b32_e32 v59, v2
	v_mov_b32_e32 v60, v2
	v_mov_b32_e32 v61, v2
	v_mov_b32_e32 v62, v2
	v_mov_b32_e32 v63, v2
	v_mov_b32_e32 v64, v2
	v_mov_b32_e32 v65, v2
	v_mov_b32_e32 v66, v2
	v_mov_b32_e32 v67, v2
	v_mov_b32_e32 v68, v2
	v_mov_b32_e32 v69, v2
	v_mov_b32_e32 v70, v2
	v_mov_b32_e32 v71, v2
	v_mov_b32_e32 v72, v2
	v_mov_b32_e32 v73, v2
	v_mov_b32_e32 v82, v2
	v_mov_b32_e32 v83, v2
	v_mov_b32_e32 v84, v2
	v_mov_b32_e32 v85, v2
	v_mov_b32_e32 v86, v2
	v_mov_b32_e32 v87, v2
	v_mov_b32_e32 v88, v2
	v_mov_b32_e32 v89, v2
	v_mov_b32_e32 v98, v2
	v_mov_b32_e32 v99, v2
	v_mov_b32_e32 v100, v2
	v_mov_b32_e32 v101, v2
	v_mov_b32_e32 v102, v2
	v_mov_b32_e32 v103, v2
	v_mov_b32_e32 v104, v2
	v_mov_b32_e32 v105, v2
	v_mov_b32_e32 v114, v2
	v_mov_b32_e32 v115, v2
	v_mov_b32_e32 v116, v2
	v_mov_b32_e32 v117, v2
	v_mov_b32_e32 v118, v2
	v_mov_b32_e32 v119, v2
	v_mov_b32_e32 v120, v2
	v_mov_b32_e32 v121, v2
	v_mov_b32_e32 v74, v2
	v_mov_b32_e32 v75, v2
	v_mov_b32_e32 v76, v2
	v_mov_b32_e32 v77, v2
	v_mov_b32_e32 v78, v2
	v_mov_b32_e32 v79, v2
	v_mov_b32_e32 v80, v2
	v_mov_b32_e32 v81, v2
	v_mov_b32_e32 v90, v2
	v_mov_b32_e32 v91, v2
	v_mov_b32_e32 v92, v2
	v_mov_b32_e32 v93, v2
	v_mov_b32_e32 v94, v2
	v_mov_b32_e32 v95, v2
	v_mov_b32_e32 v96, v2
	v_mov_b32_e32 v97, v2
	v_mov_b32_e32 v106, v2
	v_mov_b32_e32 v107, v2
	v_mov_b32_e32 v108, v2
	v_mov_b32_e32 v109, v2
	v_mov_b32_e32 v110, v2
	v_mov_b32_e32 v111, v2
	v_mov_b32_e32 v112, v2
	v_mov_b32_e32 v113, v2
	v_mov_b32_e32 v122, v2
	v_mov_b32_e32 v123, v2
	v_mov_b32_e32 v124, v2
	v_mov_b32_e32 v125, v2
	v_mov_b32_e32 v126, v2
	v_mov_b32_e32 v127, v2
	v_mov_b32_e32 v128, v2
	v_mov_b32_e32 v129, v2
	.p2alignl 6, 3212836864

; template <class Epi, class Sched, bool ALIGN_EPI = false, bool SP2 = false>
; __device__ __forceinline__ void gemm_phase(PG8_LAS unsigned char* lds, const Gemm g, const Sched& S, const Epi& E, int wave0) {
;     ...
;         const bool has_next = S.next(ui + 1, nxt);
;         const char* nA = has_next ? gA + (size_t)nxt.pm * tstep + (size_t)nxt.pz * g.azs : cA; const char* nB = has_next ? gB + (size_t)nxt.pn * tstep + (size_t)nxt.pz * g.bzs : cB;
;         for (int t = 0; t < nt; t += 2) {
;             const bool last = (t == nt - 2);
;             const char* a1 = cA + (size_t)(t + 1) * kstep;
;             const char* a2 = last ? nA : cA + (size_t)(t + 2) * kstep; const char* b2 = last ? nB : cB + (size_t)(t + 2) * kstep;
;             const char* a3 = a2 + kstep; const char* b3 = b2 + kstep;
.LBB0_1197:
	s_ashr_i32 s39, s38, 31
	s_lshl_b64 s[28:29], s[38:39], 21
	s_add_u32 s40, s2, s28
	s_addc_u32 s41, s3, s29
	s_and_b64 s[28:29], s[0:1], exec
	s_cselect_b32 s39, s41, s7
	s_cselect_b32 s47, s40, s6
	s_ashr_i32 s31, s30, 31
	s_lshl_b64 s[28:29], s[30:31], 21
	s_add_u32 s42, s48, s28
	s_addc_u32 s43, s49, s29
	s_and_b64 s[28:29], s[0:1], exec
	s_cselect_b32 s31, s43, s5
	s_cselect_b32 s60, s42, s4
	s_add_u32 s6, s6, 0x100080
	s_addc_u32 s7, s7, 0
	s_add_u32 s61, s4, 0x100
	s_addc_u32 s62, s5, 0
	s_mov_b32 s63, -2
	s_waitcnt vmcnt(0)
	.p2alignl 6, 3212836864
